# gates packed fma + attention trims + mad_u32_u24 + tr-reads before K reads + s_mov hoist (no merge epilogue change)
# baseline (speedup 1.0000x reference)
.LBB0_787:
	s_cmp_eq_u32 s0, 1
	s_cselect_b64 s[6:7], -1, 0
	s_and_b64 s[8:9], s[46:47], s[6:7]
	s_and_b64 s[8:9], s[8:9], exec
	s_cselect_b32 s53, 2, 0
	s_cmp_eq_u32 s0, 2
	s_cselect_b64 s[8:9], -1, 0
	s_and_b64 s[8:9], s[88:89], s[8:9]
	s_and_b64 s[8:9], s[8:9], exec
	s_cselect_b32 s52, 2, 4
	s_cmp_ge_u32 s53, s52
	s_cbranch_scc1 .LBB0_801
	s_lshl_b32 s8, s53, 5
	v_add_u32_e32 v32, s54, v208
	v_or_b32_e32 v34, s8, v201
	v_mad_u32_u24 v34, v34, s3, v32
	ds_read_b128 v[144:147], v34
	ds_read_b128 v[148:151], v34 offset:64
	ds_read_b128 v[140:143], v34 offset:2304
	ds_read_b128 v[136:139], v34 offset:2368
	s_cmp_lg_u32 s0, 0
	s_cselect_b64 s[86:87], -1, 0
	s_and_b64 s[6:7], s[6:7], exec
	s_cselect_b32 s54, 1, -1
	v_or_b32_e32 v35, s8, v243
	s_lshl_b32 s84, s54, 4
	s_lshl_b32 s73, s54, 5
	v_subrev_u32_e32 v34, s8, v214
	v_mul_u32_u24_e32 v35, 0xa0, v35
	s_lshl_b32 s55, s54, 1
	s_sub_i32 s85, 0, s84
	s_sub_i32 s0, 0, s73
	v_mul_lo_u32 v34, s54, v34
	v_add3_u32 v35, s61, v35, v215
	v_add_u32_e32 v35, 0xfffff5a0, v35
	s_mov_b32 s62, s60
	s_mov_b32 s63, s60
	s_mov_b32 s61, s60
	s_branch .LBB0_790
.LBB0_789:
	v_exp_f32_e32 v37, v192
	v_exp_f32_e32 v38, v196
	v_exp_f32_e32 v39, v193
	v_exp_f32_e32 v196, v197
	v_exp_f32_e32 v193, v194
	v_exp_f32_e32 v194, v195
	v_cvt_pk_bf16_f32 v192, v37, v39
	v_exp_f32_e32 v37, v180
	v_exp_f32_e32 v39, v181
	v_cvt_pk_bf16_f32 v193, v193, v194
	v_cvt_pk_bf16_f32 v194, v38, v196
	v_exp_f32_e32 v38, v188
	v_exp_f32_e32 v188, v189
	v_exp_f32_e32 v181, v182
	v_exp_f32_e32 v182, v183
	v_exp_f32_e32 v197, v198
	v_exp_f32_e32 v195, v199
	v_cvt_pk_bf16_f32 v180, v37, v39
	v_cvt_pk_bf16_f32 v181, v181, v182
	v_cvt_pk_bf16_f32 v182, v38, v188
	v_exp_f32_e32 v37, v156
	v_exp_f32_e32 v38, v184
	v_exp_f32_e32 v39, v157
	v_exp_f32_e32 v184, v185
	v_exp_f32_e32 v157, v158
	v_exp_f32_e32 v158, v159
	v_cvt_pk_bf16_f32 v195, v197, v195
	v_mov_b64_e32 v[198:199], s[62:63]
	v_mov_b64_e32 v[196:197], s[60:61]
	v_exp_f32_e32 v189, v190
	v_exp_f32_e32 v183, v191
	v_exp_f32_e32 v185, v186
	v_exp_f32_e32 v159, v187
	v_cvt_pk_bf16_f32 v156, v37, v39
	v_cvt_pk_bf16_f32 v157, v157, v158
	v_cvt_pk_bf16_f32 v158, v38, v184
	v_exp_f32_e32 v37, v152
	v_exp_f32_e32 v38, v172
	v_exp_f32_e32 v39, v153
	v_exp_f32_e32 v172, v173
	v_exp_f32_e32 v153, v154
	v_exp_f32_e32 v173, v174
	v_exp_f32_e32 v154, v155
	v_exp_f32_e32 v155, v175
	v_cvt_pk_bf16_f32 v183, v189, v183
	v_cvt_pk_bf16_f32 v159, v185, v159
	v_cvt_pk_bf16_f32 v152, v37, v39
	v_cvt_pk_bf16_f32 v153, v153, v154
	v_cvt_pk_bf16_f32 v154, v38, v172
	v_cvt_pk_bf16_f32 v155, v173, v155
	v_mfma_f32_16x16x32_bf16 v[116:119], v[196:199], v[192:195], v[116:119]
	v_subrev_u32_e32 v34, s73, v34
	v_add_u32_e32 v35, 0x1400, v35
	s_andn2_b64 vcc, exec, s[34:35]
	v_mfma_f32_16x16x32_bf16 v[64:67], v[196:199], v[180:183], v[64:67]
	v_mfma_f32_16x16x32_bf16 v[44:47], v[196:199], v[156:159], v[44:47]
	v_mfma_f32_16x16x32_bf16 v[16:19], v[196:199], v[152:155], v[16:19]
	s_waitcnt lgkmcnt(10)
	v_mfma_f32_16x16x32_bf16 v[96:99], v[168:171], v[192:195], v[96:99]
	v_mfma_f32_16x16x32_bf16 v[60:63], v[168:171], v[180:183], v[60:63]
	v_mfma_f32_16x16x32_bf16 v[40:43], v[168:171], v[156:159], v[40:43]
	v_mfma_f32_16x16x32_bf16 v[8:11], v[168:171], v[152:155], v[8:11]
	s_waitcnt lgkmcnt(8)
	v_mfma_f32_16x16x32_bf16 v[68:71], v[160:163], v[192:195], v[68:71]
	v_mfma_f32_16x16x32_bf16 v[48:51], v[160:163], v[180:183], v[48:51]
	v_mfma_f32_16x16x32_bf16 v[20:23], v[160:163], v[156:159], v[20:23]
	v_mfma_f32_16x16x32_bf16 v[0:3], v[160:163], v[152:155], v[0:3]
	s_waitcnt lgkmcnt(6)
	v_mfma_f32_16x16x32_bf16 v[92:95], v[176:179], v[192:195], v[92:95]
	v_mfma_f32_16x16x32_bf16 v[56:59], v[176:179], v[180:183], v[56:59]
	v_mfma_f32_16x16x32_bf16 v[28:31], v[176:179], v[156:159], v[28:31]
	v_mfma_f32_16x16x32_bf16 v[12:15], v[176:179], v[152:155], v[12:15]
	s_waitcnt lgkmcnt(4)
	v_mfma_f32_16x16x32_bf16 v[80:83], v[164:167], v[192:195], v[80:83]
	v_mfma_f32_16x16x32_bf16 v[52:55], v[164:167], v[180:183], v[52:55]
	v_mfma_f32_16x16x32_bf16 v[24:27], v[164:167], v[156:159], v[24:27]
	v_mfma_f32_16x16x32_bf16 v[4:7], v[164:167], v[152:155], v[4:7]
	s_cbranch_vccz .LBB0_801
.LBB0_790:
	s_waitcnt lgkmcnt(3)
	v_mfma_f32_16x16x32_bf16 v[152:155], v[144:147], v[72:75], v[228:231]
	s_waitcnt lgkmcnt(2)
	v_mfma_f32_16x16x32_bf16 v[192:195], v[148:151], v[76:79], v[152:155]
	v_mfma_f32_16x16x32_bf16 v[152:155], v[144:147], v[84:87], v[232:235]
	v_mfma_f32_16x16x32_bf16 v[180:183], v[148:151], v[88:91], v[152:155]
	s_mov_b32 s6, s53
	s_add_i32 s53, s53, 1
	s_cmp_ge_u32 s53, s52
	v_mfma_f32_16x16x32_bf16 v[152:155], v[144:147], v[100:103], v[248:251]
	s_cselect_b64 s[34:35], -1, 0
	s_cmp_lt_u32 s53, s52
	s_cselect_b32 s6, s53, s6
	v_mfma_f32_16x16x32_bf16 v[144:147], v[144:147], v[108:111], v[220:223]
	v_lshl_or_b32 v37, s6, 5, v201
	v_mad_u32_u24 v38, v37, s3, v32
	v_mfma_f32_16x16x32_bf16 v[156:159], v[148:151], v[104:107], v[152:155]
	v_mfma_f32_16x16x32_bf16 v[152:155], v[148:151], v[112:115], v[144:147]
	s_waitcnt lgkmcnt(1)
	v_mfma_f32_16x16x32_bf16 v[144:147], v[140:143], v[72:75], v[228:231]
	s_waitcnt lgkmcnt(0)
	v_mfma_f32_16x16x32_bf16 v[196:199], v[136:139], v[76:79], v[144:147]
	v_mfma_f32_16x16x32_bf16 v[144:147], v[140:143], v[84:87], v[232:235]
	v_mfma_f32_16x16x32_bf16 v[188:191], v[136:139], v[88:91], v[144:147]
	v_mfma_f32_16x16x32_bf16 v[144:147], v[140:143], v[100:103], v[248:251]
	v_mfma_f32_16x16x32_bf16 v[140:143], v[140:143], v[108:111], v[220:223]
	v_mfma_f32_16x16x32_bf16 v[184:187], v[136:139], v[104:107], v[144:147]
	ds_read_b64_tr_b16 v[168:169], v35
	ds_read_b64_tr_b16 v[170:171], v35 offset:2560
	ds_read_b64_tr_b16 v[160:161], v35 offset:32
	ds_read_b64_tr_b16 v[162:163], v35 offset:2592
	ds_read_b64_tr_b16 v[176:177], v35 offset:64
	ds_read_b64_tr_b16 v[178:179], v35 offset:2624
	ds_read_b64_tr_b16 v[164:165], v35 offset:96
	ds_read_b64_tr_b16 v[166:167], v35 offset:2656
	ds_read_b128 v[144:147], v38
	ds_read_b128 v[148:151], v38 offset:64
	v_mfma_f32_16x16x32_bf16 v[172:175], v[136:139], v[112:115], v[140:143]
	s_nop 2
	ds_read_b128 v[140:143], v38 offset:2304
	ds_read_b128 v[136:139], v38 offset:2368
	s_andn2_b64 vcc, exec, s[86:87]
	s_cbranch_vccnz .LBB0_792
	s_mul_i32 s30, s54, 0xffffffd0
	v_mov_b32_e32 v38, s4
	v_cmp_lt_i32_e64 s[30:31], s30, v34
	s_mul_i32 s10, s54, 3
	s_mul_i32 s16, s54, -15
	v_cndmask_b32_e64 v152, v152, v38, s[30:31]
	s_mul_i32 s30, s54, 0xffffffd1
	v_cmp_ge_i32_e64 s[30:31], s30, v34
	s_mul_i32 s18, s54, -14
	s_mul_i32 s20, s54, -13
	v_cndmask_b32_e64 v153, v241, v153, s[30:31]
	s_mul_i32 s30, s54, 0xffffffd2
	v_cmp_ge_i32_e64 s[30:31], s30, v34
	s_mul_i32 s24, s54, 0xffffffe1
	s_mul_i32 s26, s54, 0xffffffe2
	v_cndmask_b32_e64 v154, v241, v154, s[30:31]
	s_mul_i32 s30, s54, 0xffffffd3
	v_cmp_ge_i32_e64 s[30:31], s30, v34
	s_mul_i32 s28, s54, 0xffffffe3
	v_cmp_lt_i32_e32 vcc, 0, v34
	v_cndmask_b32_e64 v155, v241, v155, s[30:31]
	v_cmp_lt_i32_e64 s[30:31], s84, v34
	v_cmp_lt_i32_e64 s[6:7], s54, v34
	v_cmp_lt_i32_e64 s[8:9], s55, v34
	v_cndmask_b32_e64 v196, v196, v38, s[30:31]
	s_mul_i32 s30, s54, 17
	v_cmp_ge_i32_e64 s[30:31], s30, v34
	v_cmp_lt_i32_e64 s[10:11], s10, v34
	v_cmp_lt_i32_e64 s[12:13], s85, v34
	v_cndmask_b32_e64 v197, v241, v197, s[30:31]
	s_mul_i32 s30, s54, 18
	v_cmp_ge_i32_e64 s[30:31], s30, v34
	v_cmp_lt_i32_e64 s[16:17], s16, v34
	v_cmp_lt_i32_e64 s[18:19], s18, v34
	v_cndmask_b32_e64 v198, v241, v198, s[30:31]
	s_mul_i32 s30, s54, 19
	v_cmp_lt_i32_e64 s[20:21], s20, v34
	v_cmp_lt_i32_e64 s[22:23], s0, v34
	v_cmp_lt_i32_e64 s[24:25], s24, v34
	v_cmp_lt_i32_e64 s[26:27], s26, v34
	v_cmp_lt_i32_e64 s[28:29], s28, v34
	v_cmp_ge_i32_e64 s[30:31], s30, v34
	v_cndmask_b32_e32 v192, v192, v38, vcc
	v_cndmask_b32_e64 v193, v193, v241, s[6:7]
	v_cndmask_b32_e64 v194, v194, v241, s[8:9]
	v_cndmask_b32_e64 v195, v195, v241, s[10:11]
	v_cndmask_b32_e64 v180, v180, v38, s[12:13]
	v_cndmask_b32_e64 v181, v181, v241, s[16:17]
	v_cndmask_b32_e64 v182, v182, v241, s[18:19]
	v_cndmask_b32_e64 v183, v183, v241, s[20:21]
	v_cndmask_b32_e64 v156, v156, v38, s[22:23]
	v_cndmask_b32_e64 v157, v157, v241, s[24:25]
	v_cndmask_b32_e64 v158, v158, v241, s[26:27]
	v_cndmask_b32_e64 v159, v159, v241, s[28:29]
	v_cndmask_b32_e64 v199, v241, v199, s[30:31]
	v_cndmask_b32_e32 v188, v188, v38, vcc
	v_cndmask_b32_e64 v189, v189, v241, s[6:7]
	v_cndmask_b32_e64 v190, v190, v241, s[8:9]
	v_cndmask_b32_e64 v191, v191, v241, s[10:11]
	v_cndmask_b32_e64 v184, v184, v38, s[12:13]
	v_cndmask_b32_e64 v185, v185, v241, s[16:17]
	v_cndmask_b32_e64 v186, v186, v241, s[18:19]
	v_cndmask_b32_e64 v187, v187, v241, s[20:21]
	v_cndmask_b32_e64 v172, v172, v38, s[22:23]
	v_cndmask_b32_e64 v173, v173, v241, s[24:25]
	v_cndmask_b32_e64 v174, v174, v241, s[26:27]
	v_cndmask_b32_e64 v175, v175, v241, s[28:29]

.LBB0_801:
	s_waitcnt lgkmcnt(0)
	s_andn2_b64 vcc, exec, s[74:75]
	s_xor_b32 s90, s90, 1
	s_cbranch_vccz .LBB0_803
	s_mov_b32 s16, s66
	s_mov_b32 s0, s91
	s_branch .LBB0_764
